# hyena short-conv loop: prefetch wait moved behind the second store (vmcnt(2)), longer overlap window
# baseline (speedup 1.0000x reference)
.LBB0_844:
	s_mul_i32 s8, s44, 0x4100
	s_add_i32 s8, s8, 16
	v_lshlrev_b32_e32 v86, 2, v227
	v_add3_u32 v142, s8, v230, v86
	v_and_b32_e32 v87, 0xffff0000, v30
	v_lshlrev_b32_e32 v86, 16, v30
	v_pk_fma_f32 v[86:87], v[134:135], v[86:87], v[114:115]
	v_and_b32_e32 v99, 0xffff0000, v22
	v_lshlrev_b32_e32 v98, 16, v22
	v_pk_fma_f32 v[86:87], v[82:83], v[98:99], v[86:87]
	v_and_b32_e32 v99, 0xffff0000, v26
	v_lshlrev_b32_e32 v98, 16, v26
	v_pk_fma_f32 v[86:87], v[94:95], v[98:99], v[86:87]
	v_and_b32_e32 v99, 0xffff0000, v46
	v_lshlrev_b32_e32 v98, 16, v46
	v_pk_fma_f32 v[98:99], v[118:119], v[98:99], v[106:107]
	v_and_b32_e32 v123, 0xffff0000, v42
	v_lshlrev_b32_e32 v122, 16, v42
	v_pk_fma_f32 v[98:99], v[158:159], v[122:123], v[98:99]
	v_and_b32_e32 v123, 0xffff0000, v50
	v_lshlrev_b32_e32 v122, 16, v50
	v_pk_fma_f32 v[98:99], v[154:155], v[122:123], v[98:99]
	v_lshlrev_b32_e32 v26, 16, v47
	v_pk_mul_f32 v[86:87], v[98:99], v[86:87]
	ds_write2_b32 v142, v86, v87 offset1:1
	v_and_b32_e32 v87, 0xffff0000, v31
	v_lshlrev_b32_e32 v86, 16, v31
	v_pk_fma_f32 v[30:31], v[136:137], v[86:87], v[116:117]
	v_and_b32_e32 v87, 0xffff0000, v23
	v_lshlrev_b32_e32 v86, 16, v23
	v_pk_fma_f32 v[22:23], v[84:85], v[86:87], v[30:31]
	v_and_b32_e32 v31, 0xffff0000, v27
	v_lshlrev_b32_e32 v30, 16, v27
	v_and_b32_e32 v27, 0xffff0000, v47
	v_pk_fma_f32 v[22:23], v[96:97], v[30:31], v[22:23]
	v_pk_fma_f32 v[26:27], v[120:121], v[26:27], v[108:109]
	v_and_b32_e32 v31, 0xffff0000, v43
	v_lshlrev_b32_e32 v30, 16, v43
	v_pk_fma_f32 v[26:27], v[160:161], v[30:31], v[26:27]
	v_and_b32_e32 v31, 0xffff0000, v51
	v_lshlrev_b32_e32 v30, 16, v51
	v_pk_fma_f32 v[26:27], v[156:157], v[30:31], v[26:27]
	s_and_b32 s6, s3, 0xffffffc0
	v_pk_mul_f32 v[22:23], v[26:27], v[22:23]
	ds_write2_b32 v142, v22, v23 offset0:2 offset1:3
	v_lshlrev_b32_e32 v23, 16, v11
	v_lshlrev_b32_e32 v22, 16, v10
	v_and_b32_e32 v11, 0xffff0000, v11
	v_and_b32_e32 v10, 0xffff0000, v10
	v_pk_fma_f32 v[22:23], v[216:217], v[22:23], v[214:215]
	v_lshlrev_b32_e32 v27, 16, v7
	v_lshlrev_b32_e32 v26, 16, v6
	v_pk_fma_f32 v[10:11], v[204:205], v[10:11], v[202:203]
	v_and_b32_e32 v7, 0xffff0000, v7
	v_and_b32_e32 v6, 0xffff0000, v6
	v_pk_fma_f32 v[22:23], v[212:213], v[26:27], v[22:23]
	v_lshlrev_b32_e32 v27, 16, v3
	v_lshlrev_b32_e32 v26, 16, v2
	v_pk_fma_f32 v[6:7], v[208:209], v[6:7], v[10:11]
	v_and_b32_e32 v3, 0xffff0000, v3
	v_and_b32_e32 v2, 0xffff0000, v2
	v_pk_fma_f32 v[2:3], v[206:207], v[2:3], v[6:7]
	v_and_b32_e32 v7, 0xffff0000, v32
	v_lshlrev_b32_e32 v6, 16, v32
	v_pk_fma_f32 v[6:7], v[130:131], v[6:7], v[102:103]
	v_and_b32_e32 v11, 0xffff0000, v24
	v_lshlrev_b32_e32 v10, 16, v24
	v_pk_fma_f32 v[6:7], v[138:139], v[10:11], v[6:7]
	v_and_b32_e32 v11, 0xffff0000, v28
	v_lshlrev_b32_e32 v10, 16, v28
	v_pk_fma_f32 v[6:7], v[146:147], v[10:11], v[6:7]
	v_and_b32_e32 v11, 0xffff0000, v48
	v_lshlrev_b32_e32 v10, 16, v48
	v_pk_fma_f32 v[22:23], v[210:211], v[26:27], v[22:23]
	v_pk_fma_f32 v[10:11], v[162:163], v[10:11], v[150:151]
	v_and_b32_e32 v27, 0xffff0000, v44
	v_lshlrev_b32_e32 v26, 16, v44
	v_pk_fma_f32 v[10:11], v[166:167], v[26:27], v[10:11]
	v_and_b32_e32 v27, 0xffff0000, v52
	v_lshlrev_b32_e32 v26, 16, v52
	v_pk_fma_f32 v[10:11], v[170:171], v[26:27], v[10:11]
	v_lshlrev_b32_e32 v24, 16, v45
	v_pk_mul_f32 v[6:7], v[10:11], v[6:7]
	ds_write2_b32 v142, v6, v7 offset0:4 offset1:5
	v_and_b32_e32 v7, 0xffff0000, v33
	v_lshlrev_b32_e32 v6, 16, v33
	v_pk_fma_f32 v[6:7], v[132:133], v[6:7], v[104:105]
	v_and_b32_e32 v11, 0xffff0000, v25
	v_lshlrev_b32_e32 v10, 16, v25
	v_pk_fma_f32 v[6:7], v[140:141], v[10:11], v[6:7]
	v_and_b32_e32 v11, 0xffff0000, v29
	v_lshlrev_b32_e32 v10, 16, v29
	v_pk_fma_f32 v[6:7], v[148:149], v[10:11], v[6:7]
	v_and_b32_e32 v11, 0xffff0000, v49
	v_lshlrev_b32_e32 v10, 16, v49
	v_pk_fma_f32 v[10:11], v[164:165], v[10:11], v[152:153]
	v_and_b32_e32 v25, 0xffff0000, v45
	v_pk_fma_f32 v[10:11], v[168:169], v[24:25], v[10:11]
	v_and_b32_e32 v25, 0xffff0000, v53
	v_lshlrev_b32_e32 v24, 16, v53
	v_pk_fma_f32 v[10:11], v[172:173], v[24:25], v[10:11]
	v_mov_b32_e32 v175, v14
	v_pk_mul_f32 v[6:7], v[10:11], v[6:7]
	ds_write2_b32 v142, v6, v7 offset0:6 offset1:7
	v_lshlrev_b32_e32 v7, 16, v13
	v_lshlrev_b32_e32 v6, 16, v12
	v_pk_fma_f32 v[6:7], v[192:193], v[6:7], v[190:191]
	v_lshlrev_b32_e32 v11, 16, v9
	v_lshlrev_b32_e32 v10, 16, v8
	v_pk_fma_f32 v[6:7], v[196:197], v[10:11], v[6:7]
	v_lshlrev_b32_e32 v11, 16, v5
	v_lshlrev_b32_e32 v10, 16, v4
	v_pk_fma_f32 v[6:7], v[194:195], v[10:11], v[6:7]
	v_and_b32_e32 v11, 0xffff0000, v13
	v_and_b32_e32 v10, 0xffff0000, v12
	v_pk_fma_f32 v[10:11], v[184:185], v[10:11], v[16:17]
	v_and_b32_e32 v9, 0xffff0000, v9
	v_and_b32_e32 v8, 0xffff0000, v8
	v_pk_fma_f32 v[8:9], v[188:189], v[8:9], v[10:11]
	v_and_b32_e32 v5, 0xffff0000, v5
	v_and_b32_e32 v4, 0xffff0000, v4
	v_pk_fma_f32 v[4:5], v[186:187], v[4:5], v[8:9]
	v_bfe_u32 v9, v22, 16, 1
	v_bfe_u32 v11, v6, 16, 1
	v_bfe_u32 v12, v7, 16, 1
	v_add3_u32 v9, v22, v9, s67
	v_bfe_u32 v16, v2, 16, 1
	v_add_u32_e32 v8, s6, v226
	v_add3_u32 v7, v7, v12, s67
	v_add3_u32 v6, v6, v11, s67
	v_lshrrev_b32_e32 v9, 16, v9
	v_bfe_u32 v11, v5, 16, 1
	v_bfe_u32 v12, v4, 16, 1
	v_add3_u32 v2, v2, v16, s67
	v_bfe_u32 v10, v23, 16, 1
	v_lshrrev_b32_e32 v6, 16, v6
	v_lshrrev_b32_e32 v7, 16, v7
	v_add3_u32 v4, v4, v12, s67
	v_add3_u32 v5, v5, v11, s67
	v_and_or_b32 v2, v2, s66, v9
	v_ashrrev_i32_e32 v9, 31, v8
	v_add3_u32 v10, v23, v10, s67
	v_bfe_u32 v13, v3, 16, 1
	v_and_or_b32 v5, v5, s66, v7
	v_and_or_b32 v4, v4, s66, v6
	v_lshlrev_b64 v[6:7], 11, v[8:9]
	v_lshrrev_b32_e32 v10, 16, v10
	v_add3_u32 v3, v3, v13, s67
	v_lshl_add_u64 v[6:7], s[12:13], 0, v[6:7]
	v_lshlrev_b32_e32 v8, 1, v15
	v_mov_b32_e32 v9, v14
	v_and_or_b32 v3, v3, s66, v10
	v_lshl_add_u64 v[6:7], v[6:7], 0, v[8:9]
	global_store_dwordx4 v[6:7], v[2:5], off
	s_waitcnt lgkmcnt(0)
	s_barrier
	v_lshlrev_b32_e32 v2, 2, v226
	v_add3_u32 v6, s8, v231, v2
	ds_read2_b32 v[2:3], v6 offset1:65
	s_waitcnt lgkmcnt(0)
	v_bfe_u32 v4, v2, 16, 1
	v_add3_u32 v2, v2, v4, s67
	ds_read2_b32 v[4:5], v6 offset0:130 offset1:195
	v_bfe_u32 v7, v3, 16, 1
	v_lshrrev_b32_e32 v2, 16, v2
	v_add3_u32 v3, v3, v7, s67
	v_and_or_b32 v2, v3, s66, v2
	s_waitcnt lgkmcnt(0)
	v_bfe_u32 v3, v4, 16, 1
	v_add3_u32 v3, v4, v3, s67
	v_add_u32_e32 v4, 0x400, v6
	ds_read2_b32 v[6:7], v4 offset0:4 offset1:69
	v_bfe_u32 v8, v5, 16, 1
	v_lshrrev_b32_e32 v3, 16, v3
	v_add3_u32 v5, v5, v8, s67
	ds_read2_b32 v[8:9], v4 offset0:134 offset1:199
	v_and_or_b32 v3, v5, s66, v3
	s_waitcnt lgkmcnt(1)
	v_bfe_u32 v5, v6, 16, 1
	v_add3_u32 v5, v6, v5, s67
	v_lshrrev_b32_e32 v4, 16, v5
	v_bfe_u32 v5, v7, 16, 1
	v_add3_u32 v5, v7, v5, s67
	v_and_or_b32 v4, v5, s66, v4
	s_waitcnt lgkmcnt(0)
	v_bfe_u32 v5, v8, 16, 1
	v_add3_u32 v5, v8, v5, s67
	v_bfe_u32 v6, v9, 16, 1
	v_lshrrev_b32_e32 v5, 16, v5
	v_add3_u32 v6, v9, v6, s67
	v_and_or_b32 v5, v6, s66, v5
	v_add_u32_e32 v6, s7, v226
	v_mul_u32_u24_e32 v6, 0x5000, v6
	v_lshlrev_b32_e32 v6, 1, v6
	v_mov_b32_e32 v7, v14
	v_lshl_add_u64 v[6:7], s[14:15], 0, v[6:7]
	s_ashr_i32 s7, s6, 31
	v_lshl_add_u64 v[6:7], s[6:7], 1, v[6:7]
	v_lshl_add_u64 v[6:7], v[6:7], 0, v[174:175]
	global_store_dwordx4 v[6:7], v[2:5], off
	s_waitcnt vmcnt(2)
	v_mov_b64_e32 v[46:47], v[78:79]
	v_mov_b64_e32 v[30:31], v[58:59]
	v_mov_b64_e32 v[10:11], v[34:35]
	v_mov_b64_e32 v[42:43], v[74:75]
	v_mov_b64_e32 v[22:23], v[54:55]
	v_mov_b64_e32 v[6:7], v[18:19]
	v_mov_b64_e32 v[26:27], v[62:63]
	v_mov_b64_e32 v[2:3], v[38:39]
	s_xor_b32 s44, s44, 1
	s_add_i32 s3, s3, s47
	s_add_i32 s50, s50, s51
	s_andn2_b64 vcc, exec, s[56:57]
	v_mov_b64_e32 v[48:49], v[80:81]
	v_mov_b64_e32 v[32:33], v[60:61]
	v_mov_b64_e32 v[12:13], v[36:37]
	v_mov_b64_e32 v[44:45], v[76:77]
	v_mov_b64_e32 v[24:25], v[56:57]
	v_mov_b64_e32 v[8:9], v[20:21]
	v_mov_b64_e32 v[28:29], v[64:65]
	v_mov_b64_e32 v[4:5], v[40:41]
	s_mov_b32 s34, s69
	v_mov_b32_e32 v50, v126
	v_mov_b32_e32 v51, v127
	v_mov_b32_e32 v52, v128
	v_mov_b32_e32 v53, v129
	s_cbranch_vccz .LBB0_861
